# rec_fix carry composition: SGPR-base loads, (c mod 32) chunks in one laddered batch then full 32-chunk batches (was 32/8/1-chunk round trips)
# speedup vs baseline: 1.0164x; 1.0005x over previous
; __device__ __forceinline__ void rec_fix_phase(LAS unsigned char* lds, const RecArgs& a, int bid, int G, int tid_in) {
;     ...
;         float carry = 0.f;
;         {
;             const float* pa = a.SUMA + (size_t)(b * NCH) * 512 + tid; const float* ph = a.SUMH + (size_t)(b * NCH) * 512 + tid;
;             int cc = 0;
;             for (; cc + 32 <= c; cc += 32) { float A_[32], H_[32];
; #pragma unroll
;                 for (int i = 0; i < 32; ++i) { A_[i] = pa[(size_t)(cc + i) * 512]; H_[i] = ph[(size_t)(cc + i) * 512]; }
; #pragma unroll
;                 for (int i = 0; i < 32; ++i) carry = A_[i] * carry + H_[i]; }
;             for (; cc + 8 <= c; cc += 8) { float A_[8], H_[8];
; #pragma unroll
;                 for (int i = 0; i < 8; ++i) { A_[i] = pa[(size_t)(cc + i) * 512]; H_[i] = ph[(size_t)(cc + i) * 512]; }
; #pragma unroll
;                 for (int i = 0; i < 8; ++i) carry = A_[i] * carry + H_[i]; }
;             for (; cc < c; ++cc) carry = pa[(size_t)cc * 512] * carry + ph[(size_t)cc * 512];
;         }
.LBB0_546:
	s_ashr_i32 s2, s49, 7
	s_add_i32 s3, s49, 0xfffffe00
	s_and_b32 s6, s49, 0x7f
	s_cmpk_lt_i32 s49, 0x200
	s_cselect_b32 s2, s2, s3
	s_mul_i32 s8, s2, 0x81
	s_cselect_b32 s3, s6, 0x80
	s_ashr_i32 s9, s8, 31
	v_lshlrev_b32_e32 v5, 2, v212
	v_mov_b32_e32 v4, 0
	s_and_b32 s6, s3, 31
	s_cmp_eq_u32 s6, 0
	s_cbranch_scc1 .Lfix_full_setup
	s_lshl_b64 s[10:11], s[8:9], 11
	s_add_u32 s10, s10, s24
	s_addc_u32 s11, s11, s25
	s_add_u32 s10, s10, 0x3700000
	s_addc_u32 s11, s11, 0
	s_add_u32 s14, s10, 0x200000
	s_addc_u32 s15, s11, 0
	global_load_dword v2, v5, s[10:11]
	global_load_dword v3, v5, s[14:15]
	s_cmp_le_u32 s6, 1
	s_cbranch_scc1 .Lfix_pl_done
	global_load_dword v6, v5, s[10:11] offset:2048
	global_load_dword v7, v5, s[14:15] offset:2048
	s_add_u32 s10, s10, 0x1000
	s_addc_u32 s11, s11, 0
	s_add_u32 s14, s14, 0x1000
	s_addc_u32 s15, s15, 0
	s_cmp_le_u32 s6, 2
	s_cbranch_scc1 .Lfix_pl_done
	global_load_dword v8, v5, s[10:11]
	global_load_dword v9, v5, s[14:15]
	s_cmp_le_u32 s6, 3
	s_cbranch_scc1 .Lfix_pl_done
	global_load_dword v10, v5, s[10:11] offset:2048
	global_load_dword v11, v5, s[14:15] offset:2048
	s_add_u32 s10, s10, 0x1000
	s_addc_u32 s11, s11, 0
	s_add_u32 s14, s14, 0x1000
	s_addc_u32 s15, s15, 0
	s_cmp_le_u32 s6, 4
	s_cbranch_scc1 .Lfix_pl_done
	global_load_dword v12, v5, s[10:11]
	global_load_dword v13, v5, s[14:15]
	s_cmp_le_u32 s6, 5
	s_cbranch_scc1 .Lfix_pl_done
	global_load_dword v14, v5, s[10:11] offset:2048
	global_load_dword v15, v5, s[14:15] offset:2048
	s_add_u32 s10, s10, 0x1000
	s_addc_u32 s11, s11, 0
	s_add_u32 s14, s14, 0x1000
	s_addc_u32 s15, s15, 0
	s_cmp_le_u32 s6, 6
	s_cbranch_scc1 .Lfix_pl_done
	global_load_dword v16, v5, s[10:11]
	global_load_dword v17, v5, s[14:15]
	s_cmp_le_u32 s6, 7
	s_cbranch_scc1 .Lfix_pl_done
	global_load_dword v18, v5, s[10:11] offset:2048
	global_load_dword v19, v5, s[14:15] offset:2048
	s_add_u32 s10, s10, 0x1000
	s_addc_u32 s11, s11, 0
	s_add_u32 s14, s14, 0x1000
	s_addc_u32 s15, s15, 0
	s_cmp_le_u32 s6, 8
	s_cbranch_scc1 .Lfix_pl_done
	global_load_dword v20, v5, s[10:11]
	global_load_dword v21, v5, s[14:15]
	s_cmp_le_u32 s6, 9
	s_cbranch_scc1 .Lfix_pl_done
	global_load_dword v22, v5, s[10:11] offset:2048
	global_load_dword v23, v5, s[14:15] offset:2048
	s_add_u32 s10, s10, 0x1000
	s_addc_u32 s11, s11, 0
	s_add_u32 s14, s14, 0x1000
	s_addc_u32 s15, s15, 0
	s_cmp_le_u32 s6, 10
	s_cbranch_scc1 .Lfix_pl_done
	global_load_dword v24, v5, s[10:11]
	global_load_dword v25, v5, s[14:15]
	s_cmp_le_u32 s6, 11
	s_cbranch_scc1 .Lfix_pl_done
	global_load_dword v26, v5, s[10:11] offset:2048
	global_load_dword v27, v5, s[14:15] offset:2048
	s_add_u32 s10, s10, 0x1000
	s_addc_u32 s11, s11, 0
	s_add_u32 s14, s14, 0x1000
	s_addc_u32 s15, s15, 0
	s_cmp_le_u32 s6, 12
	s_cbranch_scc1 .Lfix_pl_done
	global_load_dword v28, v5, s[10:11]
	global_load_dword v29, v5, s[14:15]
	s_cmp_le_u32 s6, 13
	s_cbranch_scc1 .Lfix_pl_done
	global_load_dword v30, v5, s[10:11] offset:2048
	global_load_dword v31, v5, s[14:15] offset:2048
	s_add_u32 s10, s10, 0x1000
	s_addc_u32 s11, s11, 0
	s_add_u32 s14, s14, 0x1000
	s_addc_u32 s15, s15, 0
	s_cmp_le_u32 s6, 14
	s_cbranch_scc1 .Lfix_pl_done
	global_load_dword v32, v5, s[10:11]
	global_load_dword v33, v5, s[14:15]
	s_cmp_le_u32 s6, 15
	s_cbranch_scc1 .Lfix_pl_done
	global_load_dword v34, v5, s[10:11] offset:2048
	global_load_dword v35, v5, s[14:15] offset:2048
	s_add_u32 s10, s10, 0x1000
	s_addc_u32 s11, s11, 0
	s_add_u32 s14, s14, 0x1000
	s_addc_u32 s15, s15, 0
	s_cmp_le_u32 s6, 16
	s_cbranch_scc1 .Lfix_pl_done
	global_load_dword v36, v5, s[10:11]
	global_load_dword v37, v5, s[14:15]
	s_cmp_le_u32 s6, 17
	s_cbranch_scc1 .Lfix_pl_done
	global_load_dword v38, v5, s[10:11] offset:2048
	global_load_dword v39, v5, s[14:15] offset:2048
	s_add_u32 s10, s10, 0x1000
	s_addc_u32 s11, s11, 0
	s_add_u32 s14, s14, 0x1000
	s_addc_u32 s15, s15, 0
	s_cmp_le_u32 s6, 18
	s_cbranch_scc1 .Lfix_pl_done
	global_load_dword v40, v5, s[10:11]
	global_load_dword v41, v5, s[14:15]
	s_cmp_le_u32 s6, 19
	s_cbranch_scc1 .Lfix_pl_done
	global_load_dword v42, v5, s[10:11] offset:2048
	global_load_dword v43, v5, s[14:15] offset:2048
	s_add_u32 s10, s10, 0x1000
	s_addc_u32 s11, s11, 0
	s_add_u32 s14, s14, 0x1000
	s_addc_u32 s15, s15, 0
	s_cmp_le_u32 s6, 20
	s_cbranch_scc1 .Lfix_pl_done
	global_load_dword v44, v5, s[10:11]
	global_load_dword v45, v5, s[14:15]
	s_cmp_le_u32 s6, 21
	s_cbranch_scc1 .Lfix_pl_done
	global_load_dword v46, v5, s[10:11] offset:2048
	global_load_dword v47, v5, s[14:15] offset:2048
	s_add_u32 s10, s10, 0x1000
	s_addc_u32 s11, s11, 0
	s_add_u32 s14, s14, 0x1000
	s_addc_u32 s15, s15, 0
	s_cmp_le_u32 s6, 22
	s_cbranch_scc1 .Lfix_pl_done
	global_load_dword v48, v5, s[10:11]
	global_load_dword v49, v5, s[14:15]
	s_cmp_le_u32 s6, 23
	s_cbranch_scc1 .Lfix_pl_done
	global_load_dword v50, v5, s[10:11] offset:2048
	global_load_dword v51, v5, s[14:15] offset:2048
	s_add_u32 s10, s10, 0x1000
	s_addc_u32 s11, s11, 0
	s_add_u32 s14, s14, 0x1000
	s_addc_u32 s15, s15, 0
	s_cmp_le_u32 s6, 24
	s_cbranch_scc1 .Lfix_pl_done
	global_load_dword v52, v5, s[10:11]
	global_load_dword v53, v5, s[14:15]
	s_cmp_le_u32 s6, 25
	s_cbranch_scc1 .Lfix_pl_done
	global_load_dword v54, v5, s[10:11] offset:2048
	global_load_dword v55, v5, s[14:15] offset:2048
	s_add_u32 s10, s10, 0x1000
	s_addc_u32 s11, s11, 0
	s_add_u32 s14, s14, 0x1000
	s_addc_u32 s15, s15, 0
	s_cmp_le_u32 s6, 26
	s_cbranch_scc1 .Lfix_pl_done
	global_load_dword v56, v5, s[10:11]
	global_load_dword v57, v5, s[14:15]
	s_cmp_le_u32 s6, 27
	s_cbranch_scc1 .Lfix_pl_done
	global_load_dword v58, v5, s[10:11] offset:2048
	global_load_dword v59, v5, s[14:15] offset:2048
	s_add_u32 s10, s10, 0x1000
	s_addc_u32 s11, s11, 0
	s_add_u32 s14, s14, 0x1000
	s_addc_u32 s15, s15, 0
	s_cmp_le_u32 s6, 28
	s_cbranch_scc1 .Lfix_pl_done
	global_load_dword v60, v5, s[10:11]
	global_load_dword v61, v5, s[14:15]
	s_cmp_le_u32 s6, 29
	s_cbranch_scc1 .Lfix_pl_done
	global_load_dword v62, v5, s[10:11] offset:2048
	global_load_dword v63, v5, s[14:15] offset:2048
	s_add_u32 s10, s10, 0x1000
	s_addc_u32 s11, s11, 0
	s_add_u32 s14, s14, 0x1000
	s_addc_u32 s15, s15, 0
	s_cmp_le_u32 s6, 30
	s_cbranch_scc1 .Lfix_pl_done
	global_load_dword v64, v5, s[10:11]
	global_load_dword v65, v5, s[14:15]
; __device__ __forceinline__ void rec_fix_phase(LAS unsigned char* lds, const RecArgs& a, int bid, int G, int tid_in) {
;     ...
;             for (; cc + 32 <= c; cc += 32) { float A_[32], H_[32];
; #pragma unroll
;                 for (int i = 0; i < 32; ++i) { A_[i] = pa[(size_t)(cc + i) * 512]; H_[i] = ph[(size_t)(cc + i) * 512]; }
; #pragma unroll
;                 for (int i = 0; i < 32; ++i) carry = A_[i] * carry + H_[i]; }
;             for (; cc + 8 <= c; cc += 8) { float A_[8], H_[8];
; #pragma unroll
;                 for (int i = 0; i < 8; ++i) { A_[i] = pa[(size_t)(cc + i) * 512]; H_[i] = ph[(size_t)(cc + i) * 512]; }
; #pragma unroll
;                 for (int i = 0; i < 8; ++i) carry = A_[i] * carry + H_[i]; }
;             for (; cc < c; ++cc) carry = pa[(size_t)cc * 512] * carry + ph[(size_t)cc * 512];
;         }
.Lfix_pl_done:
	s_waitcnt vmcnt(0)
	v_fma_f32 v4, v2, v4, v3
	s_cmp_le_u32 s6, 1
	s_cbranch_scc1 .Lfix_pf_done
	v_fma_f32 v4, v6, v4, v7
	s_cmp_le_u32 s6, 2
	s_cbranch_scc1 .Lfix_pf_done
	v_fma_f32 v4, v8, v4, v9
	s_cmp_le_u32 s6, 3
	s_cbranch_scc1 .Lfix_pf_done
	v_fma_f32 v4, v10, v4, v11
	s_cmp_le_u32 s6, 4
	s_cbranch_scc1 .Lfix_pf_done
	v_fma_f32 v4, v12, v4, v13
	s_cmp_le_u32 s6, 5
	s_cbranch_scc1 .Lfix_pf_done
	v_fma_f32 v4, v14, v4, v15
	s_cmp_le_u32 s6, 6
	s_cbranch_scc1 .Lfix_pf_done
	v_fma_f32 v4, v16, v4, v17
	s_cmp_le_u32 s6, 7
	s_cbranch_scc1 .Lfix_pf_done
	v_fma_f32 v4, v18, v4, v19
	s_cmp_le_u32 s6, 8
	s_cbranch_scc1 .Lfix_pf_done
	v_fma_f32 v4, v20, v4, v21
	s_cmp_le_u32 s6, 9
	s_cbranch_scc1 .Lfix_pf_done
	v_fma_f32 v4, v22, v4, v23
	s_cmp_le_u32 s6, 10
	s_cbranch_scc1 .Lfix_pf_done
	v_fma_f32 v4, v24, v4, v25
	s_cmp_le_u32 s6, 11
	s_cbranch_scc1 .Lfix_pf_done
	v_fma_f32 v4, v26, v4, v27
	s_cmp_le_u32 s6, 12
	s_cbranch_scc1 .Lfix_pf_done
	v_fma_f32 v4, v28, v4, v29
	s_cmp_le_u32 s6, 13
	s_cbranch_scc1 .Lfix_pf_done
	v_fma_f32 v4, v30, v4, v31
	s_cmp_le_u32 s6, 14
	s_cbranch_scc1 .Lfix_pf_done
	v_fma_f32 v4, v32, v4, v33
	s_cmp_le_u32 s6, 15
	s_cbranch_scc1 .Lfix_pf_done
	v_fma_f32 v4, v34, v4, v35
	s_cmp_le_u32 s6, 16
	s_cbranch_scc1 .Lfix_pf_done
	v_fma_f32 v4, v36, v4, v37
	s_cmp_le_u32 s6, 17
	s_cbranch_scc1 .Lfix_pf_done
	v_fma_f32 v4, v38, v4, v39
	s_cmp_le_u32 s6, 18
	s_cbranch_scc1 .Lfix_pf_done
	v_fma_f32 v4, v40, v4, v41
	s_cmp_le_u32 s6, 19
	s_cbranch_scc1 .Lfix_pf_done
	v_fma_f32 v4, v42, v4, v43
	s_cmp_le_u32 s6, 20
	s_cbranch_scc1 .Lfix_pf_done
	v_fma_f32 v4, v44, v4, v45
	s_cmp_le_u32 s6, 21
	s_cbranch_scc1 .Lfix_pf_done
	v_fma_f32 v4, v46, v4, v47
	s_cmp_le_u32 s6, 22
	s_cbranch_scc1 .Lfix_pf_done
	v_fma_f32 v4, v48, v4, v49
	s_cmp_le_u32 s6, 23
	s_cbranch_scc1 .Lfix_pf_done
	v_fma_f32 v4, v50, v4, v51
	s_cmp_le_u32 s6, 24
	s_cbranch_scc1 .Lfix_pf_done
	v_fma_f32 v4, v52, v4, v53
	s_cmp_le_u32 s6, 25
	s_cbranch_scc1 .Lfix_pf_done
	v_fma_f32 v4, v54, v4, v55
	s_cmp_le_u32 s6, 26
	s_cbranch_scc1 .Lfix_pf_done
	v_fma_f32 v4, v56, v4, v57
	s_cmp_le_u32 s6, 27
	s_cbranch_scc1 .Lfix_pf_done
	v_fma_f32 v4, v58, v4, v59
	s_cmp_le_u32 s6, 28
	s_cbranch_scc1 .Lfix_pf_done
	v_fma_f32 v4, v60, v4, v61
	s_cmp_le_u32 s6, 29
	s_cbranch_scc1 .Lfix_pf_done
	v_fma_f32 v4, v62, v4, v63
	s_cmp_le_u32 s6, 30
	s_cbranch_scc1 .Lfix_pf_done
	v_fma_f32 v4, v64, v4, v65
.Lfix_pf_done:
.Lfix_full_setup:
	s_cmp_ge_u32 s6, s3
	s_cbranch_scc1 .LBB0_556
	s_lshl_b64 s[10:11], s[8:9], 11
	s_add_u32 s10, s10, s24
	s_addc_u32 s11, s11, s25
	s_add_u32 s10, s10, 0x3700000
	s_addc_u32 s11, s11, 0
	s_lshl_b32 s14, s6, 11
	s_add_u32 s10, s10, s14
	s_addc_u32 s11, s11, 0
	s_add_u32 s14, s10, 0x200000
	s_addc_u32 s15, s11, 0
; __device__ __forceinline__ void rec_fix_phase(LAS unsigned char* lds, const RecArgs& a, int bid, int G, int tid_in) {
;     ...
;             for (; cc + 32 <= c; cc += 32) { float A_[32], H_[32];
; #pragma unroll
;                 for (int i = 0; i < 32; ++i) { A_[i] = pa[(size_t)(cc + i) * 512]; H_[i] = ph[(size_t)(cc + i) * 512]; }
; #pragma unroll
;                 for (int i = 0; i < 32; ++i) carry = A_[i] * carry + H_[i]; }
.Lfix_full_loop:
	global_load_dword v2, v5, s[10:11]
	global_load_dword v3, v5, s[14:15]
	global_load_dword v6, v5, s[10:11] offset:2048
	global_load_dword v7, v5, s[14:15] offset:2048
	s_add_u32 s10, s10, 0x1000
	s_addc_u32 s11, s11, 0
	s_add_u32 s14, s14, 0x1000
	s_addc_u32 s15, s15, 0
	global_load_dword v8, v5, s[10:11]
	global_load_dword v9, v5, s[14:15]
	global_load_dword v10, v5, s[10:11] offset:2048
	global_load_dword v11, v5, s[14:15] offset:2048
	s_add_u32 s10, s10, 0x1000
	s_addc_u32 s11, s11, 0
	s_add_u32 s14, s14, 0x1000
	s_addc_u32 s15, s15, 0
	global_load_dword v12, v5, s[10:11]
	global_load_dword v13, v5, s[14:15]
	global_load_dword v14, v5, s[10:11] offset:2048
	global_load_dword v15, v5, s[14:15] offset:2048
	s_add_u32 s10, s10, 0x1000
	s_addc_u32 s11, s11, 0
	s_add_u32 s14, s14, 0x1000
	s_addc_u32 s15, s15, 0
	global_load_dword v16, v5, s[10:11]
	global_load_dword v17, v5, s[14:15]
	global_load_dword v18, v5, s[10:11] offset:2048
	global_load_dword v19, v5, s[14:15] offset:2048
	s_add_u32 s10, s10, 0x1000
	s_addc_u32 s11, s11, 0
	s_add_u32 s14, s14, 0x1000
	s_addc_u32 s15, s15, 0
	global_load_dword v20, v5, s[10:11]
	global_load_dword v21, v5, s[14:15]
	global_load_dword v22, v5, s[10:11] offset:2048
	global_load_dword v23, v5, s[14:15] offset:2048
	s_add_u32 s10, s10, 0x1000
	s_addc_u32 s11, s11, 0
	s_add_u32 s14, s14, 0x1000
	s_addc_u32 s15, s15, 0
	global_load_dword v24, v5, s[10:11]
	global_load_dword v25, v5, s[14:15]
	global_load_dword v26, v5, s[10:11] offset:2048
	global_load_dword v27, v5, s[14:15] offset:2048
	s_add_u32 s10, s10, 0x1000
	s_addc_u32 s11, s11, 0
	s_add_u32 s14, s14, 0x1000
	s_addc_u32 s15, s15, 0
	global_load_dword v28, v5, s[10:11]
	global_load_dword v29, v5, s[14:15]
	global_load_dword v30, v5, s[10:11] offset:2048
	global_load_dword v31, v5, s[14:15] offset:2048
	s_add_u32 s10, s10, 0x1000
	s_addc_u32 s11, s11, 0
	s_add_u32 s14, s14, 0x1000
	s_addc_u32 s15, s15, 0
	global_load_dword v32, v5, s[10:11]
	global_load_dword v33, v5, s[14:15]
	global_load_dword v34, v5, s[10:11] offset:2048
	global_load_dword v35, v5, s[14:15] offset:2048
	s_add_u32 s10, s10, 0x1000
	s_addc_u32 s11, s11, 0
	s_add_u32 s14, s14, 0x1000
	s_addc_u32 s15, s15, 0
	global_load_dword v36, v5, s[10:11]
	global_load_dword v37, v5, s[14:15]
	global_load_dword v38, v5, s[10:11] offset:2048
	global_load_dword v39, v5, s[14:15] offset:2048
	s_add_u32 s10, s10, 0x1000
	s_addc_u32 s11, s11, 0
	s_add_u32 s14, s14, 0x1000
	s_addc_u32 s15, s15, 0
	global_load_dword v40, v5, s[10:11]
	global_load_dword v41, v5, s[14:15]
	global_load_dword v42, v5, s[10:11] offset:2048
	global_load_dword v43, v5, s[14:15] offset:2048
	s_add_u32 s10, s10, 0x1000
	s_addc_u32 s11, s11, 0
	s_add_u32 s14, s14, 0x1000
	s_addc_u32 s15, s15, 0
	global_load_dword v44, v5, s[10:11]
	global_load_dword v45, v5, s[14:15]
	global_load_dword v46, v5, s[10:11] offset:2048
	global_load_dword v47, v5, s[14:15] offset:2048
	s_add_u32 s10, s10, 0x1000
	s_addc_u32 s11, s11, 0
	s_add_u32 s14, s14, 0x1000
	s_addc_u32 s15, s15, 0
	global_load_dword v48, v5, s[10:11]
	global_load_dword v49, v5, s[14:15]
	global_load_dword v50, v5, s[10:11] offset:2048
	global_load_dword v51, v5, s[14:15] offset:2048
	s_add_u32 s10, s10, 0x1000
	s_addc_u32 s11, s11, 0
	s_add_u32 s14, s14, 0x1000
	s_addc_u32 s15, s15, 0
	global_load_dword v52, v5, s[10:11]
	global_load_dword v53, v5, s[14:15]
	global_load_dword v54, v5, s[10:11] offset:2048
	global_load_dword v55, v5, s[14:15] offset:2048
	s_add_u32 s10, s10, 0x1000
	s_addc_u32 s11, s11, 0
	s_add_u32 s14, s14, 0x1000
	s_addc_u32 s15, s15, 0
	global_load_dword v56, v5, s[10:11]
	global_load_dword v57, v5, s[14:15]
	global_load_dword v58, v5, s[10:11] offset:2048
	global_load_dword v59, v5, s[14:15] offset:2048
	s_add_u32 s10, s10, 0x1000
	s_addc_u32 s11, s11, 0
	s_add_u32 s14, s14, 0x1000
	s_addc_u32 s15, s15, 0
	global_load_dword v60, v5, s[10:11]
	global_load_dword v61, v5, s[14:15]
	global_load_dword v62, v5, s[10:11] offset:2048
	global_load_dword v63, v5, s[14:15] offset:2048
	s_add_u32 s10, s10, 0x1000
	s_addc_u32 s11, s11, 0
	s_add_u32 s14, s14, 0x1000
	s_addc_u32 s15, s15, 0
	global_load_dword v64, v5, s[10:11]
	global_load_dword v65, v5, s[14:15]
	global_load_dword v66, v5, s[10:11] offset:2048
	global_load_dword v67, v5, s[14:15] offset:2048
	s_add_u32 s10, s10, 0x1000
	s_addc_u32 s11, s11, 0
	s_add_u32 s14, s14, 0x1000
	s_addc_u32 s15, s15, 0
	s_add_i32 s6, s6, 32
	s_waitcnt vmcnt(62)
	v_fma_f32 v4, v2, v4, v3
	s_waitcnt vmcnt(60)
	v_fma_f32 v4, v6, v4, v7
	s_waitcnt vmcnt(58)
	v_fma_f32 v4, v8, v4, v9
	s_waitcnt vmcnt(56)
	v_fma_f32 v4, v10, v4, v11
	s_waitcnt vmcnt(54)
	v_fma_f32 v4, v12, v4, v13
	s_waitcnt vmcnt(52)
	v_fma_f32 v4, v14, v4, v15
	s_waitcnt vmcnt(50)
	v_fma_f32 v4, v16, v4, v17
	s_waitcnt vmcnt(48)
	v_fma_f32 v4, v18, v4, v19
	s_waitcnt vmcnt(46)
	v_fma_f32 v4, v20, v4, v21
	s_waitcnt vmcnt(44)
	v_fma_f32 v4, v22, v4, v23
	s_waitcnt vmcnt(42)
	v_fma_f32 v4, v24, v4, v25
	s_waitcnt vmcnt(40)
	v_fma_f32 v4, v26, v4, v27
	s_waitcnt vmcnt(38)
	v_fma_f32 v4, v28, v4, v29
	s_waitcnt vmcnt(36)
	v_fma_f32 v4, v30, v4, v31
	s_waitcnt vmcnt(34)
	v_fma_f32 v4, v32, v4, v33
	s_waitcnt vmcnt(32)
	v_fma_f32 v4, v34, v4, v35
	s_waitcnt vmcnt(30)
	v_fma_f32 v4, v36, v4, v37
	s_waitcnt vmcnt(28)
	v_fma_f32 v4, v38, v4, v39
	s_waitcnt vmcnt(26)
	v_fma_f32 v4, v40, v4, v41
	s_waitcnt vmcnt(24)
	v_fma_f32 v4, v42, v4, v43
	s_waitcnt vmcnt(22)
	v_fma_f32 v4, v44, v4, v45
	s_waitcnt vmcnt(20)
	v_fma_f32 v4, v46, v4, v47
	s_waitcnt vmcnt(18)
	v_fma_f32 v4, v48, v4, v49
	s_waitcnt vmcnt(16)
	v_fma_f32 v4, v50, v4, v51
	s_waitcnt vmcnt(14)
	v_fma_f32 v4, v52, v4, v53
	s_waitcnt vmcnt(12)
	v_fma_f32 v4, v54, v4, v55
	s_waitcnt vmcnt(10)
	v_fma_f32 v4, v56, v4, v57
	s_waitcnt vmcnt(8)
	v_fma_f32 v4, v58, v4, v59
	s_waitcnt vmcnt(6)
	v_fma_f32 v4, v60, v4, v61
	s_waitcnt vmcnt(4)
	v_fma_f32 v4, v62, v4, v63
	s_waitcnt vmcnt(2)
	v_fma_f32 v4, v64, v4, v65
	s_waitcnt vmcnt(0)
	v_fma_f32 v4, v66, v4, v67
	s_cmp_lt_u32 s6, s3
	s_cbranch_scc1 .Lfix_full_loop
